# mla_rows: the two sequential 64-lane sum reductions of the second row use DPP (quad_perm/row_half_mirror/row_mirror) + permlane16/32 swaps instead of six ds_bpermute round trips each (bit-identical)
# baseline (speedup 1.0000x reference)
; __device__ __forceinline__ float lane_xor(float v, int lane, int o) { return __builtin_bit_cast(float, __builtin_amdgcn_ds_bpermute((lane ^ o) << 2, __builtin_bit_cast(int, v))); }
; __device__ __forceinline__ unsigned f2bf(float f) { unsigned u = __builtin_bit_cast(unsigned, f); return (u + 0x7fffu + ((u >> 16) & 1u)) >> 16; }
; __device__ __forceinline__ unsigned pk2(float lo, float hi) { return f2bf(lo) | (f2bf(hi) << 16); }
; __device__ __forceinline__ float wave_sum(float v, int lane) {
; #pragma unroll
;     for (int o = 1; o < 64; o <<= 1) v += lane_xor(v, lane, o);
;     return v;
; __device__ __forceinline__ void mla_rows(const bf16_t* U, const float* gcq, const float* gckv, const float* rope, bf16_t* XQ, bf16_t* XKV, bf16_t* KC, int gw, int ngw) {
;     ...
;             const float q0 = __builtin_bit_cast(float, cq[k].x << 16), q1 = __builtin_bit_cast(float, cq[k].x & 0xffff0000u), q2 = __builtin_bit_cast(float, cq[k].y << 16), q3 = __builtin_bit_cast(float, cq[k].y & 0xffff0000u);
;             const float k0 = __builtin_bit_cast(float, ckv[k] << 16), k1 = __builtin_bit_cast(float, ckv[k] & 0xffff0000u);
;             const float sq = wave_sum((q0 * q0 + q1 * q1) + (q2 * q2 + q3 * q3), lane), sk = wave_sum(k0 * k0 + k1 * k1, lane);
;             const float rq = 1.0f / sqrtf(sq * (1.0f / 256.0f) + EPSN), rk = 1.0f / sqrtf(sk * (1.0f / 128.0f) + EPSN);
;             u32x2 wq; wq.x = pk2(q0 * rq * gq.x, q1 * rq * gq.y); wq.y = pk2(q2 * rq * gq.z, q3 * rq * gq.w);
;             *(u32x2*)(XQ + (size_t)r * 256 + 4 * lane) = wq;
;             *(unsigned*)(XKV + (size_t)r * 128 + 2 * lane) = pk2(k0 * rk * gk0, k1 * rk * gk1);
;             const float other = lane_xor(krv[k], lane, 16);
;             const float ro = (lane & 16) ? (krv[k] * cs[k] + other * sn[k]) : (krv[k] * cs[k] - other * sn[k]);
;             if (lane < 32) { const unsigned short ob = (unsigned short)f2bf(ro); bf16_t* kc = KC + (size_t)r * 384 + 64 + lane;
;                 kc[0] = ob; kc[96] = ob; kc[192] = ob; kc[288] = ob; }
.LBB0_645:
	s_waitcnt vmcnt(0)
	v_lshlrev_b32_e32 v25, 16, v27
	v_lshlrev_b32_e32 v24, 16, v26
	v_and_b32_e32 v27, 0xffff0000, v27
	v_and_b32_e32 v26, 0xffff0000, v26
	v_pk_mul_f32 v[34:35], v[26:27], v[26:27]
	s_mov_b32 s10, 0xf800000
	v_pk_fma_f32 v[34:35], v[24:25], v[24:25], v[34:35]
	s_waitcnt lgkmcnt(0)
	v_lshlrev_b32_e32 v20, 16, v36
	v_add_f32_e32 v23, v34, v35
	v_and_b32_e32 v21, 0xffff0000, v36
	v_mov_b32_e32 v39, 0x260
	v_lshlrev_b32_e32 v22, 16, v37
	s_ashr_i32 s9, s8, 31
	s_nop 1
	v_add_f32_dpp v23, v23, v23 quad_perm:[1,0,3,2] row_mask:0xf bank_mask:0xf
	s_nop 1
	v_add_f32_dpp v23, v23, v23 quad_perm:[2,3,0,1] row_mask:0xf bank_mask:0xf
	s_nop 1
	v_add_f32_dpp v23, v23, v23 row_half_mirror row_mask:0xf bank_mask:0xf
	s_nop 1
	v_add_f32_dpp v23, v23, v23 row_mirror row_mask:0xf bank_mask:0xf
	v_mov_b32_e32 v34, v23
	s_nop 1
	v_permlane16_swap_b32_e32 v23, v34
	v_add_f32_e32 v23, v23, v34
	v_mov_b32_e32 v34, v23
	s_nop 1
	v_permlane32_swap_b32_e32 v23, v34
	v_add_f32_e32 v23, v23, v34
	v_fmamk_f32 v23, v23, 0x3b800000, v218
	v_cmp_gt_f32_e32 vcc, s10, v23
	v_mul_f32_e32 v34, 0x4f800000, v23
	s_nop 0
	v_cndmask_b32_e32 v23, v23, v34, vcc
	v_sqrt_f32_e32 v34, v23
	s_nop 0
	v_add_u32_e32 v35, -1, v34
	v_fma_f32 v36, -v35, v34, v23
	v_cmp_ge_f32_e64 s[6:7], 0, v36
	v_add_u32_e32 v36, 1, v34
	s_nop 0
	v_cndmask_b32_e64 v35, v34, v35, s[6:7]
	v_fma_f32 v34, -v36, v34, v23
	v_cmp_lt_f32_e64 s[6:7], 0, v34
	s_nop 1
	v_cndmask_b32_e64 v34, v35, v36, s[6:7]
	v_mul_f32_e32 v35, 0x37800000, v34
	v_cndmask_b32_e32 v34, v34, v35, vcc
	v_cmp_class_f32_e32 vcc, v23, v39
	s_nop 1
	v_cndmask_b32_e32 v23, v34, v23, vcc
	v_div_scale_f32 v34, s[6:7], v23, v23, 1.0
	v_rcp_f32_e32 v35, v34
	s_lshl_b64 s[6:7], s[8:9], 9
	v_fma_f32 v36, -v34, v35, 1.0
	v_fmac_f32_e32 v35, v36, v35
	v_div_scale_f32 v36, vcc, 1.0, v23, 1.0
	v_mul_f32_e32 v37, v36, v35
	v_fma_f32 v38, -v34, v37, v36
	v_fmac_f32_e32 v37, v38, v35
	v_fma_f32 v34, -v34, v37, v36
	v_div_fmas_f32 v34, v34, v35, v37
	v_div_fixup_f32 v34, v34, v23, 1.0
	v_pk_mul_f32 v[24:25], v[34:35], v[24:25] op_sel_hi:[0,1]
	v_pk_mul_f32 v[24:25], v[2:3], v[24:25]
	v_pk_mul_f32 v[26:27], v[34:35], v[26:27] op_sel_hi:[0,1]
	v_pk_mul_f32 v[26:27], v[14:15], v[26:27]
	v_and_b32_sdwa v23, v25, v219 dst_sel:DWORD dst_unused:UNUSED_PAD src0_sel:WORD_1 src1_sel:DWORD
	v_and_b32_sdwa v34, v24, v219 dst_sel:DWORD dst_unused:UNUSED_PAD src0_sel:WORD_1 src1_sel:DWORD
	v_add3_u32 v24, v24, v34, s44
	v_add3_u32 v23, v25, v23, s44
	v_and_b32_sdwa v25, v27, v219 dst_sel:DWORD dst_unused:UNUSED_PAD src0_sel:WORD_1 src1_sel:DWORD
	v_and_b32_sdwa v34, v26, v219 dst_sel:DWORD dst_unused:UNUSED_PAD src0_sel:WORD_1 src1_sel:DWORD
	v_add3_u32 v25, v27, v25, s44
	v_add3_u32 v26, v26, v34, s44
	v_and_b32_e32 v25, 0xffff0000, v25
	v_and_b32_e32 v26, 0xffff0000, v26
	v_or_b32_sdwa v25, v25, v23 dst_sel:DWORD dst_unused:UNUSED_PAD src0_sel:DWORD src1_sel:WORD_1
	v_or_b32_sdwa v24, v26, v24 dst_sel:DWORD dst_unused:UNUSED_PAD src0_sel:DWORD src1_sel:WORD_1
	v_lshl_add_u64 v[26:27], v[12:13], 0, s[6:7]
	flat_store_dwordx2 v[26:27], v[24:25]
	v_pk_mul_f32 v[24:25], v[20:21], v[20:21]
	s_nop 0
	v_add_f32_e32 v23, v24, v25
	s_nop 1
	v_add_f32_dpp v23, v23, v23 quad_perm:[1,0,3,2] row_mask:0xf bank_mask:0xf
	s_nop 1
	v_add_f32_dpp v23, v23, v23 quad_perm:[2,3,0,1] row_mask:0xf bank_mask:0xf
	s_nop 1
	v_add_f32_dpp v23, v23, v23 row_half_mirror row_mask:0xf bank_mask:0xf
	s_nop 1
	v_add_f32_dpp v23, v23, v23 row_mirror row_mask:0xf bank_mask:0xf
	v_mov_b32_e32 v24, v23
	s_nop 1
	v_permlane16_swap_b32_e32 v23, v24
	v_add_f32_e32 v23, v23, v24
	v_mov_b32_e32 v24, v23
	s_nop 1
	v_permlane32_swap_b32_e32 v23, v24
	v_add_f32_e32 v23, v23, v24
	v_fmamk_f32 v23, v23, 0x3c000000, v218
	v_cmp_gt_f32_e32 vcc, s10, v23
	v_mul_f32_e32 v24, 0x4f800000, v23
	s_nop 0
	v_cndmask_b32_e32 v23, v23, v24, vcc
	v_sqrt_f32_e32 v24, v23
	s_nop 0
	v_add_u32_e32 v25, -1, v24
	v_fma_f32 v26, -v25, v24, v23
	v_cmp_ge_f32_e64 s[6:7], 0, v26
	v_add_u32_e32 v26, 1, v24
	s_nop 0
	v_cndmask_b32_e64 v25, v24, v25, s[6:7]
	v_fma_f32 v24, -v26, v24, v23
	v_cmp_lt_f32_e64 s[6:7], 0, v24
	s_nop 1
	v_cndmask_b32_e64 v24, v25, v26, s[6:7]
	v_mul_f32_e32 v25, 0x37800000, v24
	v_cndmask_b32_e32 v24, v24, v25, vcc
	v_cmp_class_f32_e32 vcc, v23, v39
	s_nop 1
	v_cndmask_b32_e32 v23, v24, v23, vcc
	v_div_scale_f32 v24, s[6:7], v23, v23, 1.0
	v_rcp_f32_e32 v25, v24
	s_lshl_b64 s[6:7], s[8:9], 8
	v_fma_f32 v26, -v24, v25, 1.0
	v_fmac_f32_e32 v25, v26, v25
	v_div_scale_f32 v26, vcc, 1.0, v23, 1.0
	v_mul_f32_e32 v27, v26, v25
	v_fma_f32 v34, -v24, v27, v26
	v_fmac_f32_e32 v27, v34, v25
	v_fma_f32 v24, -v24, v27, v26
	v_div_fmas_f32 v24, v24, v25, v27
	v_div_fixup_f32 v24, v24, v23, 1.0
	v_pk_mul_f32 v[20:21], v[24:25], v[20:21] op_sel_hi:[0,1]
	v_pk_mul_f32 v[20:21], v[6:7], v[20:21]
	s_nop 0
	v_and_b32_sdwa v24, v20, v219 dst_sel:DWORD dst_unused:UNUSED_PAD src0_sel:WORD_1 src1_sel:DWORD
	v_and_b32_sdwa v23, v21, v219 dst_sel:DWORD dst_unused:UNUSED_PAD src0_sel:WORD_1 src1_sel:DWORD
	v_add3_u32 v20, v20, v24, s44
	v_add3_u32 v21, v21, v23, s44
	v_lshrrev_b32_e32 v20, 16, v20
	v_and_or_b32 v23, v21, s49, v20
	v_lshl_add_u64 v[20:21], v[10:11], 0, s[6:7]
	flat_store_dword v[20:21], v23
	ds_bpermute_b32 v20, v32, v22
	s_and_saveexec_b64 s[6:7], s[4:5]
	s_cbranch_execz .LBB0_640
	s_waitcnt lgkmcnt(0)
	v_mul_f32_e32 v19, v19, v20
	v_cndmask_b32_e64 v19, v19, -v19, s[0:1]
	v_fmac_f32_e32 v19, v17, v22
	v_bfe_u32 v17, v19, 16, 1
	v_add3_u32 v17, v19, v17, s44
	v_mov_b32_e32 v19, 0x300
	v_lshrrev_b32_e32 v17, 16, v17
	v_mad_i64_i32 v[20:21], s[8:9], s8, v19, v[4:5]
	flat_store_short v[20:21], v17 offset:128
	flat_store_short v[20:21], v17 offset:320
	flat_store_short v[20:21], v17 offset:512
	flat_store_short v[20:21], v17 offset:704
	s_branch .LBB0_640
